# attention steady loop: V LDS-DMA moved from the block between the MFMA phases to just ahead of the closing wait and barrier (K DMA stays)
# speedup vs baseline: 1.0067x; 1.0042x over previous
;   #define RESC() do{ if(resc){ asm volatile("s_waitcnt lgkmcnt(0)":::"memory"); \
;       _Pragma("unroll") for(int d_=0;d_<2;++d_) _Pragma("unroll") for(int r=0;r<16;++r)o[d_][r]*=wsf[crow(r,hi)]; } }while(0)
;   #define ROT() do{sl_prev=sl_cur;sl_cur=sl_next;sl_next=(sl_next==(NSLOT-1)*SLOTB)?0:sl_next+SLOTB;}while(0)
;   #define WAIT_STEADY() WAIT_BAR(3)
;   #define WAIT_STEADY() WAIT_BAR(2)
; template<int THRL,bool NOMAX> __device__ __forceinline__ void attn_unit(int b,int h,int qb,int t0,const bf16*Q,const bf16*__restrict__ KV,const bf16*__restrict__ GA,bf16*O,char*shm){
;     ...
;   for(;t+5<NT;t+=2){
;     STEP(pB0,pB1,pA0,pA1,t,true,true,true);     WAIT_STEADY(); RESC(); ROT();
.LBB0_479:
	v_add_u32_e32 v179, s16, v2
	ds_read_b64_tr_b16 v[198:199], v179 offset:24576
	ds_read_b64_tr_b16 v[200:201], v179 offset:25088
	v_add_f32_e32 v88, v68, v69
	v_add_f32_e32 v88, v70, v88
	v_add_f32_e32 v88, v71, v88
	v_add_f32_e32 v88, v72, v88
	v_add_f32_e32 v88, v73, v88
	v_cvt_pk_bf16_f32 v160, v68, v69
	v_cvt_pk_bf16_f32 v161, v70, v71
	v_mfma_f32_32x32x16_bf16 v[100:115], v[84:87], v[152:155], v[36:51]
	ds_read_b64_tr_b16 v[202:203], v179 offset:28672
	ds_read_b64_tr_b16 v[204:205], v179 offset:29184
	v_add_f32_e32 v68, v74, v88
	v_mfma_f32_32x32x16_bf16 v[84:99], v[168:171], v[152:155], v[36:51]
	v_add_f32_e32 v68, v75, v68
	v_add_f32_e32 v68, v76, v68
	v_add_f32_e32 v140, v77, v68
	v_cvt_pk_bf16_f32 v162, v72, v73
	v_cvt_pk_bf16_f32 v163, v74, v75
	ds_read_b64_tr_b16 v[68:69], v179 offset:25600
	ds_read_b64_tr_b16 v[70:71], v179 offset:26112
	v_add_f32_e32 v72, v78, v140
	v_add_f32_e32 v72, v79, v72
	v_add_f32_e32 v72, v80, v72
	v_add_f32_e32 v140, v81, v72
	v_cvt_pk_bf16_f32 v156, v76, v77
	v_cvt_pk_bf16_f32 v157, v78, v79
	v_mfma_f32_32x32x16_bf16 v[100:115], v[172:175], v[144:147], v[100:115]
	ds_read_b64_tr_b16 v[72:73], v179 offset:29696
	ds_read_b64_tr_b16 v[74:75], v179 offset:30208
	v_mfma_f32_32x32x16_bf16 v[84:99], v[164:167], v[144:147], v[84:99]
	v_add_f32_e32 v76, v82, v140
	v_add_f32_e32 v76, v83, v76
	v_add_f32_e32 v76, v52, v76
	v_add_f32_e32 v140, v53, v76
	v_cvt_pk_bf16_f32 v158, v80, v81
	v_cvt_pk_bf16_f32 v159, v82, v83
	ds_read_b64_tr_b16 v[76:77], v179 offset:26624
	ds_read_b64_tr_b16 v[78:79], v179 offset:27136
	v_add_f32_e32 v80, v54, v140
	v_add_f32_e32 v80, v55, v80
	v_add_f32_e32 v80, v56, v80
	v_add_f32_e32 v80, v57, v80
	v_cvt_pk_bf16_f32 v148, v52, v53
	v_cvt_pk_bf16_f32 v149, v54, v55
	v_mfma_f32_32x32x16_bf16 v[100:115], v[128:131], v[136:139], v[100:115]
	ds_read_b64_tr_b16 v[52:53], v179 offset:30720
	ds_read_b64_tr_b16 v[54:55], v179 offset:31232
	v_mfma_f32_32x32x16_bf16 v[84:99], v[124:127], v[136:139], v[84:99]
	v_add_f32_e32 v80, v58, v80
	v_add_f32_e32 v80, v59, v80
	v_add_f32_e32 v80, v60, v80
	v_add_f32_e32 v80, v61, v80
	v_cvt_pk_bf16_f32 v150, v56, v57
	v_cvt_pk_bf16_f32 v151, v58, v59
	ds_read_b64_tr_b16 v[56:57], v179 offset:27648
	ds_read_b64_tr_b16 v[58:59], v179 offset:28160
	v_add_f32_e32 v80, v62, v80
	v_add_f32_e32 v80, v63, v80
	v_add_f32_e32 v80, v64, v80
	v_add_f32_e32 v80, v65, v80
	v_cvt_pk_bf16_f32 v140, v60, v61
	v_cvt_pk_bf16_f32 v141, v62, v63
	v_mfma_f32_32x32x16_bf16 v[100:115], v[120:123], v[132:135], v[100:115]
	ds_read_b64_tr_b16 v[60:61], v179 offset:31744
	ds_read_b64_tr_b16 v[62:63], v179 offset:32256
	v_mfma_f32_32x32x16_bf16 v[84:99], v[116:119], v[132:135], v[84:99]
	v_add_f32_e32 v80, v66, v80
	v_add_f32_e32 v80, v67, v80
	v_add_f32_e32 v179, 0, v80
	v_cvt_pk_bf16_f32 v142, v64, v65
	v_cvt_pk_bf16_f32 v143, v66, v67
	s_add_i32 s16, s21, 0x4000
	s_and_b32 s16, s16, 0xfc000
	s_lshl_b32 s16, s16, 1
	v_lshl_add_u64 v[218:219], v[182:183], 0, s[16:17]
	s_add_i32 m0, s22, s9
	s_nop 0
	global_load_lds_dwordx4 v[218:219], off
	s_waitcnt lgkmcnt(4)
	v_mfma_f32_32x32x16_bf16 v[4:19], v[160:163], v[198:201], v[4:19]
	v_exp_f32_e32 v100, v100
	v_exp_f32_e32 v101, v101
	v_exp_f32_e32 v102, v102
	v_exp_f32_e32 v103, v103
	v_mfma_f32_32x32x16_bf16 v[20:35], v[160:163], v[202:205], v[20:35]
	v_exp_f32_e32 v104, v104
	v_exp_f32_e32 v105, v105
	v_exp_f32_e32 v106, v106
	v_exp_f32_e32 v107, v107
	v_add_u32_e32 v80, s15, v189
	ds_read_b128 v[64:67], v80
	ds_read_b128 v[120:123], v80 offset:512
	v_mfma_f32_32x32x16_bf16 v[4:19], v[156:159], v[68:71], v[4:19]
	v_exp_f32_e32 v108, v108
	v_exp_f32_e32 v109, v109
	v_exp_f32_e32 v110, v110
	v_exp_f32_e32 v111, v111
	ds_read_b128 v[124:127], v80 offset:2048
	ds_read_b128 v[128:131], v80 offset:2560
	v_mfma_f32_32x32x16_bf16 v[20:35], v[156:159], v[72:75], v[20:35]
	v_exp_f32_e32 v112, v112
	v_exp_f32_e32 v113, v113
	v_exp_f32_e32 v114, v114
	v_exp_f32_e32 v115, v115
	ds_read_b128 v[164:167], v80 offset:4096
	ds_read_b128 v[168:171], v80 offset:4608
	v_mfma_f32_32x32x16_bf16 v[4:19], v[148:151], v[76:79], v[4:19]
	v_exp_f32_e32 v84, v84
	v_exp_f32_e32 v85, v85
	v_exp_f32_e32 v86, v86
	v_exp_f32_e32 v87, v87
	ds_read_b128 v[172:175], v80 offset:6144
	ds_read_b128 v[116:119], v80 offset:6656
	v_mfma_f32_32x32x16_bf16 v[20:35], v[148:151], v[52:55], v[20:35]
	v_exp_f32_e32 v88, v88
	v_exp_f32_e32 v89, v89
	v_exp_f32_e32 v90, v90
	v_exp_f32_e32 v91, v91
	s_waitcnt lgkmcnt(8)
	v_mfma_f32_32x32x16_bf16 v[4:19], v[140:143], v[56:59], v[4:19]
	v_exp_f32_e32 v92, v92
	v_exp_f32_e32 v93, v93
	v_exp_f32_e32 v94, v94
	v_exp_f32_e32 v95, v95
	v_mfma_f32_32x32x16_bf16 v[20:35], v[140:143], v[60:63], v[20:35]
	v_exp_f32_e32 v96, v96
	v_exp_f32_e32 v97, v97
	v_exp_f32_e32 v98, v98
	v_exp_f32_e32 v99, v99
	s_add_i32 s16, s20, 0xffff4000
	s_and_b32 s16, s16, 0xfc000
	s_lshl_b32 s16, s16, 1
	v_lshl_add_u64 v[218:219], v[180:181], 0, s[16:17]
	s_add_i32 m0, s15, s8
	s_nop 0
	global_load_lds_dwordx4 v[218:219], off
	s_waitcnt vmcnt(2) lgkmcnt(0)
	s_barrier
;   #define RESC() do{ if(resc){ asm volatile("s_waitcnt lgkmcnt(0)":::"memory"); \
;       _Pragma("unroll") for(int d_=0;d_<2;++d_) _Pragma("unroll") for(int r=0;r<16;++r)o[d_][r]*=wsf[crow(r,hi)]; } }while(0)
;   #define ROT() do{sl_prev=sl_cur;sl_cur=sl_next;sl_next=(sl_next==(NSLOT-1)*SLOTB)?0:sl_next+SLOTB;}while(0)
;   #define WAIT_STEADY() WAIT_BAR(3)
;   #define WAIT_STEADY() WAIT_BAR(2)
; template<int THRL,bool NOMAX> __device__ __forceinline__ void attn_unit(int b,int h,int qb,int t0,const bf16*Q,const bf16*__restrict__ KV,const bf16*__restrict__ GA,bf16*O,char*shm){
;     ...
;   for(;t+5<NT;t+=2){
;     STEP(pB0,pB1,pA0,pA1,t,true,true,true);     WAIT_STEADY(); RESC(); ROT();
;     STEP(pA0,pA1,pB0,pB1,t+1,true,true,true);   WAIT_STEADY(); RESC(); ROT();
;   }
	s_add_i32 s16, s15, 0x2000
	s_cmpk_lg_i32 s15, 0x4000
	s_cselect_b32 s23, s16, 0
	v_add_u32_e32 v190, s22, v2
	ds_read_b64_tr_b16 v[198:199], v190 offset:24576
	ds_read_b64_tr_b16 v[200:201], v190 offset:25088
	v_mfma_f32_32x32x16_bf16 v[68:83], v[64:67], v[152:155], v[36:51]
	v_add_f32_e32 v52, v100, v101
	v_add_f32_e32 v52, v102, v52
	v_add_f32_e32 v52, v103, v52
	v_add_f32_e32 v52, v104, v52
	v_add_f32_e32 v52, v105, v52
	v_cvt_pk_bf16_f32 v160, v100, v101
	v_cvt_pk_bf16_f32 v161, v102, v103
	ds_read_b64_tr_b16 v[202:203], v190 offset:28672
	ds_read_b64_tr_b16 v[204:205], v190 offset:29184
	v_add_f32_e32 v52, v106, v52
	v_add_f32_e32 v52, v107, v52
	v_add_f32_e32 v52, v108, v52
	v_add_f32_e32 v140, v109, v52
	v_mfma_f32_32x32x16_bf16 v[52:67], v[120:123], v[152:155], v[36:51]
	v_cvt_pk_bf16_f32 v162, v104, v105
	v_cvt_pk_bf16_f32 v163, v106, v107
	ds_read_b64_tr_b16 v[100:101], v190 offset:25600
	ds_read_b64_tr_b16 v[102:103], v190 offset:26112
	v_mfma_f32_32x32x16_bf16 v[68:83], v[124:127], v[144:147], v[68:83]
	v_add_f32_e32 v104, v110, v140
	v_add_f32_e32 v104, v111, v104
	v_add_f32_e32 v104, v112, v104
	v_add_f32_e32 v120, v113, v104
	v_cvt_pk_bf16_f32 v156, v108, v109
	v_cvt_pk_bf16_f32 v157, v110, v111
	ds_read_b64_tr_b16 v[104:105], v190 offset:29696
	ds_read_b64_tr_b16 v[106:107], v190 offset:30208
	v_mfma_f32_32x32x16_bf16 v[52:67], v[128:131], v[144:147], v[52:67]
	v_add_f32_e32 v108, v114, v120
	v_add_f32_e32 v108, v115, v108
	v_add_f32_e32 v108, v84, v108
	v_add_f32_e32 v120, v85, v108
	v_cvt_pk_bf16_f32 v158, v112, v113
	v_cvt_pk_bf16_f32 v159, v114, v115
	ds_read_b64_tr_b16 v[108:109], v190 offset:26624
	ds_read_b64_tr_b16 v[110:111], v190 offset:27136
	v_mfma_f32_32x32x16_bf16 v[68:83], v[164:167], v[136:139], v[68:83]
	v_add_f32_e32 v112, v86, v120
	v_add_f32_e32 v112, v87, v112
	v_add_f32_e32 v112, v88, v112
	v_add_f32_e32 v120, v89, v112
	v_cvt_pk_bf16_f32 v148, v84, v85
	v_cvt_pk_bf16_f32 v149, v86, v87
	ds_read_b64_tr_b16 v[112:113], v190 offset:30720
	ds_read_b64_tr_b16 v[114:115], v190 offset:31232
	v_mfma_f32_32x32x16_bf16 v[52:67], v[168:171], v[136:139], v[52:67]
	v_add_f32_e32 v84, v90, v120
	v_add_f32_e32 v84, v91, v84
	v_add_f32_e32 v84, v92, v84
	v_add_f32_e32 v84, v93, v84
	v_cvt_pk_bf16_f32 v150, v88, v89
	v_cvt_pk_bf16_f32 v151, v90, v91
	ds_read_b64_tr_b16 v[88:89], v190 offset:27648
	ds_read_b64_tr_b16 v[90:91], v190 offset:28160
	v_mfma_f32_32x32x16_bf16 v[68:83], v[172:175], v[132:135], v[68:83]
	v_add_f32_e32 v84, v94, v84
	v_add_f32_e32 v84, v95, v84
	v_add_f32_e32 v84, v96, v84
	v_add_f32_e32 v84, v97, v84
	v_cvt_pk_bf16_f32 v140, v92, v93
	v_cvt_pk_bf16_f32 v141, v94, v95
	ds_read_b64_tr_b16 v[92:93], v190 offset:31744
	ds_read_b64_tr_b16 v[94:95], v190 offset:32256
	v_mfma_f32_32x32x16_bf16 v[52:67], v[116:119], v[132:135], v[52:67]
	v_add_f32_e32 v84, v98, v84
	v_add_f32_e32 v84, v99, v84
	v_add_f32_e32 v190, 0, v84
	v_cvt_pk_bf16_f32 v142, v96, v97
	v_cvt_pk_bf16_f32 v143, v98, v99
	s_and_b32 s16, s20, 0xfc000
	s_lshl_b32 s16, s16, 1
	v_lshl_add_u64 v[218:219], v[182:183], 0, s[16:17]
	s_add_i32 m0, s15, s9
	s_nop 0
	global_load_lds_dwordx4 v[218:219], off
	s_waitcnt lgkmcnt(4)
	v_mfma_f32_32x32x16_bf16 v[4:19], v[160:163], v[198:201], v[4:19]
	v_exp_f32_e32 v68, v68
	v_exp_f32_e32 v69, v69
	v_exp_f32_e32 v70, v70
	v_exp_f32_e32 v71, v71
	v_mfma_f32_32x32x16_bf16 v[20:35], v[160:163], v[202:205], v[20:35]
	v_exp_f32_e32 v72, v72
	v_exp_f32_e32 v73, v73
	v_exp_f32_e32 v74, v74
	v_exp_f32_e32 v75, v75
	v_add_u32_e32 v96, s23, v189
	ds_read_b128 v[84:87], v96
	ds_read_b128 v[168:171], v96 offset:512
	v_mfma_f32_32x32x16_bf16 v[4:19], v[156:159], v[100:103], v[4:19]
	v_exp_f32_e32 v76, v76
	v_exp_f32_e32 v77, v77
	v_exp_f32_e32 v78, v78
	v_exp_f32_e32 v79, v79
	ds_read_b128 v[172:175], v96 offset:2048
	ds_read_b128 v[164:167], v96 offset:2560
	v_mfma_f32_32x32x16_bf16 v[20:35], v[156:159], v[104:107], v[20:35]
	v_exp_f32_e32 v80, v80
	v_exp_f32_e32 v81, v81
	v_exp_f32_e32 v82, v82
	v_exp_f32_e32 v83, v83
	ds_read_b128 v[128:131], v96 offset:4096
	ds_read_b128 v[124:127], v96 offset:4608
	v_mfma_f32_32x32x16_bf16 v[4:19], v[148:151], v[108:111], v[4:19]
	v_exp_f32_e32 v52, v52
	v_exp_f32_e32 v53, v53
	v_exp_f32_e32 v54, v54
	v_exp_f32_e32 v55, v55
	ds_read_b128 v[120:123], v96 offset:6144
	ds_read_b128 v[116:119], v96 offset:6656
	v_mfma_f32_32x32x16_bf16 v[20:35], v[148:151], v[112:115], v[20:35]
	v_exp_f32_e32 v56, v56
	v_exp_f32_e32 v57, v57
	v_exp_f32_e32 v58, v58
	v_exp_f32_e32 v59, v59
	s_waitcnt lgkmcnt(8)
	v_mfma_f32_32x32x16_bf16 v[4:19], v[140:143], v[88:91], v[4:19]
	v_exp_f32_e32 v60, v60
	v_exp_f32_e32 v61, v61
	v_exp_f32_e32 v62, v62
	v_exp_f32_e32 v63, v63
	v_mfma_f32_32x32x16_bf16 v[20:35], v[140:143], v[92:95], v[20:35]
	v_exp_f32_e32 v64, v64
	v_exp_f32_e32 v65, v65
	v_exp_f32_e32 v66, v66
	v_exp_f32_e32 v67, v67
	s_add_i32 s26, s23, 0x2000
	s_and_b32 s16, s21, 0xfc000
	s_lshl_b32 s16, s16, 1
	v_lshl_add_u64 v[218:219], v[180:181], 0, s[16:17]
	s_add_i32 m0, s23, s8
	s_nop 0
	global_load_lds_dwordx4 v[218:219], off
	s_waitcnt vmcnt(2) lgkmcnt(0)
	s_barrier
	s_cmpk_lg_i32 s23, 0x4000
	v_add_f32_e32 v88, v191, v179
	s_mov_b32 s16, s15
	s_cselect_b32 s15, s26, 0
	s_add_i32 s14, s14, 2
	s_add_i32 s21, s21, 0x8000
	s_add_i32 s20, s20, 0x8000
	s_mov_b32 s22, s23
	v_add_f32_e32 v191, v88, v190
	s_cmp_gt_u32 s14, 56
	s_cbranch_scc0 .LBB0_479
;   #define RESC() do{ if(resc){ asm volatile("s_waitcnt lgkmcnt(0)":::"memory"); \
;       _Pragma("unroll") for(int d_=0;d_<2;++d_) _Pragma("unroll") for(int r=0;r<16;++r)o[d_][r]*=wsf[crow(r,hi)]; } }while(0)
;   #define ROT() do{sl_prev=sl_cur;sl_cur=sl_next;sl_next=(sl_next==(NSLOT-1)*SLOTB)?0:sl_next+SLOTB;}while(0)
;   #define ENDW(tt) do{ if((tt)+3<NT){WAIT_BAR(2);} else if((tt)+2<NT){WAIT_BAR(1);} else {WAIT_BAR(0);} }while(0)
; template<int THRL,bool NOMAX> __device__ __forceinline__ void attn_unit(int b,int h,int qb,int t0,const bf16*Q,const bf16*__restrict__ KV,const bf16*__restrict__ GA,bf16*O,char*shm){
;     ...
;   for(;t+1<NT;t+=2){
;     STEP(pB0,pB1,pA0,pA1,t,(t+3<NT),(t+1<NT),(t+1<NT));       ENDW(t);   RESC(); ROT();
	s_and_b32 s12, s12, 0x3fffffc0
	s_cmp_lg_u32 0, -1
	s_cselect_b32 s14, 0, 0
	s_add_i32 s15, s14, 0x6000
	s_lshl_b32 s12, s12, 2
	v_add_u32_e32 v88, s15, v177
	s_add_i32 s12, s12, 0
	v_add3_u32 v190, v88, v176, v178
	ds_read_b64_tr_b16 v[198:199], v2 offset:32768
	ds_read_b64_tr_b16 v[200:201], v2 offset:33280
	v_add_f32_e32 v88, v68, v69
	v_add_f32_e32 v88, v70, v88
	v_add_f32_e32 v88, v71, v88
	v_add_f32_e32 v88, v72, v88
	v_add_f32_e32 v88, v73, v88
	v_cvt_pk_bf16_f32 v160, v68, v69
	v_cvt_pk_bf16_f32 v161, v70, v71
	s_waitcnt lgkmcnt(9)
	v_mfma_f32_32x32x16_bf16 v[100:115], v[84:87], v[152:155], v[36:51]
	ds_read_b64_tr_b16 v[176:177], v2 offset:36864
	ds_read_b64_tr_b16 v[178:179], v2 offset:37376
	v_add_f32_e32 v68, v74, v88
	v_add_f32_e32 v68, v75, v68
	v_add_f32_e32 v68, v76, v68
	v_add_f32_e32 v140, v77, v68
	v_cvt_pk_bf16_f32 v162, v72, v73
	v_cvt_pk_bf16_f32 v163, v74, v75
	s_waitcnt lgkmcnt(10)
	v_mfma_f32_32x32x16_bf16 v[84:99], v[168:171], v[152:155], v[36:51]
	ds_read_b64_tr_b16 v[68:69], v2 offset:33792
	ds_read_b64_tr_b16 v[70:71], v2 offset:34304
	v_add_f32_e32 v72, v78, v140
	v_add_f32_e32 v72, v79, v72
	v_add_f32_e32 v72, v80, v72
	v_add_f32_e32 v140, v81, v72
	v_cvt_pk_bf16_f32 v156, v76, v77
	v_cvt_pk_bf16_f32 v157, v78, v79
	s_waitcnt lgkmcnt(11)
	v_mfma_f32_32x32x16_bf16 v[100:115], v[172:175], v[144:147], v[100:115]
	ds_read_b64_tr_b16 v[72:73], v2 offset:37888
	ds_read_b64_tr_b16 v[74:75], v2 offset:38400
	v_add_f32_e32 v76, v82, v140
	v_add_f32_e32 v76, v83, v76
	v_add_f32_e32 v76, v52, v76
	v_add_f32_e32 v140, v53, v76
	v_cvt_pk_bf16_f32 v158, v80, v81
	v_cvt_pk_bf16_f32 v159, v82, v83
	s_waitcnt lgkmcnt(12)
	v_mfma_f32_32x32x16_bf16 v[84:99], v[164:167], v[144:147], v[84:99]
	ds_read_b64_tr_b16 v[76:77], v2 offset:34816
	ds_read_b64_tr_b16 v[78:79], v2 offset:35328
	v_add_f32_e32 v80, v54, v140
	v_add_f32_e32 v80, v55, v80
	v_add_f32_e32 v80, v56, v80
	v_add_f32_e32 v80, v57, v80
	v_cvt_pk_bf16_f32 v148, v52, v53
	v_cvt_pk_bf16_f32 v149, v54, v55
	s_waitcnt lgkmcnt(13)
	v_mfma_f32_32x32x16_bf16 v[100:115], v[128:131], v[136:139], v[100:115]
	ds_read_b64_tr_b16 v[52:53], v2 offset:38912
	ds_read_b64_tr_b16 v[54:55], v2 offset:39424
	v_add_f32_e32 v80, v58, v80
	v_add_f32_e32 v80, v59, v80
	v_add_f32_e32 v80, v60, v80
	v_add_f32_e32 v80, v61, v80
	v_cvt_pk_bf16_f32 v150, v56, v57
	v_cvt_pk_bf16_f32 v151, v58, v59
	s_waitcnt lgkmcnt(14)
	v_mfma_f32_32x32x16_bf16 v[84:99], v[124:127], v[136:139], v[84:99]
	ds_read_b64_tr_b16 v[56:57], v2 offset:35840
	ds_read_b64_tr_b16 v[58:59], v2 offset:36352
	v_add_f32_e32 v80, v62, v80
	v_add_f32_e32 v80, v63, v80
	v_add_f32_e32 v80, v64, v80
	v_add_f32_e32 v80, v65, v80
	v_cvt_pk_bf16_f32 v140, v60, v61
	v_cvt_pk_bf16_f32 v141, v62, v63
	s_waitcnt lgkmcnt(14)
	v_mfma_f32_32x32x16_bf16 v[100:115], v[120:123], v[132:135], v[100:115]
	ds_read_b64_tr_b16 v[60:61], v2 offset:39936
	ds_read_b64_tr_b16 v[62:63], v2 offset:40448
	v_add_f32_e32 v80, v66, v80
	v_add_f32_e32 v80, v67, v80
	v_add_f32_e32 v80, 0, v80
	v_cvt_pk_bf16_f32 v142, v64, v65
	v_cvt_pk_bf16_f32 v143, v66, v67
	v_mfma_f32_32x32x16_bf16 v[84:99], v[116:119], v[132:135], v[84:99]
	v_readlane_b32 s20, v254, 56
	v_readlane_b32 s21, v254, 57
	s_mov_b32 s21, s17
	s_add_i32 s13, s14, s13
	v_lshl_add_u64 v[64:65], v[182:183], 0, s[20:21]
	s_add_i32 s14, s13, 0x4000
	s_mov_b32 s15, m0
	s_mov_b32 m0, s14
	s_nop 0
	global_load_lds_dwordx4 v[64:65], off
	s_mov_b32 m0, s15
	v_add_f32_e32 v191, v191, v80
	v_readlane_b32 s14, v254, 58
	v_readlane_b32 s15, v254, 59
	s_mov_b32 s15, s17
	s_mov_b32 s16, s14
	v_lshl_add_u64 v[64:65], v[180:181], 0, s[14:15]
	s_mov_b32 s14, m0
	s_mov_b32 m0, s8
	s_nop 0
	global_load_lds_dwordx4 v[64:65], off
	s_mov_b32 m0, s14
	v_writelane_b32 v254, s16, 58
	s_nop 1
	v_writelane_b32 v254, s17, 59
	s_waitcnt lgkmcnt(14)
	v_mfma_f32_32x32x16_bf16 v[4:19], v[160:163], v[198:201], v[4:19]
	v_exp_f32_e32 v100, v100
	v_exp_f32_e32 v101, v101
	v_exp_f32_e32 v102, v102
	v_exp_f32_e32 v103, v103
	s_waitcnt lgkmcnt(12)
	v_mfma_f32_32x32x16_bf16 v[20:35], v[160:163], v[176:179], v[20:35]
	v_exp_f32_e32 v104, v104
	v_exp_f32_e32 v105, v105
	v_exp_f32_e32 v106, v106
	v_exp_f32_e32 v107, v107
	ds_read_b128 v[64:67], v189
	ds_read_b128 v[80:83], v189 offset:512
	s_waitcnt lgkmcnt(12)
	v_mfma_f32_32x32x16_bf16 v[4:19], v[156:159], v[68:71], v[4:19]
	v_exp_f32_e32 v108, v108
	v_exp_f32_e32 v109, v109
	v_exp_f32_e32 v110, v110
	v_exp_f32_e32 v111, v111
	ds_read_b128 v[164:167], v189 offset:2048
	ds_read_b128 v[168:171], v189 offset:2560
	s_waitcnt lgkmcnt(12)
	v_mfma_f32_32x32x16_bf16 v[20:35], v[156:159], v[72:75], v[20:35]
	v_exp_f32_e32 v112, v112
	v_exp_f32_e32 v113, v113
	v_exp_f32_e32 v114, v114
	v_exp_f32_e32 v115, v115
	ds_read_b128 v[172:175], v189 offset:4096
	ds_read_b128 v[176:179], v189 offset:4608
	s_waitcnt lgkmcnt(12)
	v_mfma_f32_32x32x16_bf16 v[4:19], v[148:151], v[76:79], v[4:19]
	v_exp_f32_e32 v84, v84
	v_exp_f32_e32 v85, v85
	v_exp_f32_e32 v86, v86
	v_exp_f32_e32 v87, v87
	ds_read_b128 v[198:201], v189 offset:6144
	ds_read_b128 v[72:75], v189 offset:6656
	s_waitcnt lgkmcnt(12)
	v_mfma_f32_32x32x16_bf16 v[20:35], v[148:151], v[52:55], v[20:35]
	v_exp_f32_e32 v88, v88
	v_exp_f32_e32 v89, v89
	v_exp_f32_e32 v90, v90
	v_exp_f32_e32 v91, v91
	s_waitcnt lgkmcnt(10)
	v_mfma_f32_32x32x16_bf16 v[4:19], v[140:143], v[56:59], v[4:19]
	v_exp_f32_e32 v92, v92
	v_exp_f32_e32 v93, v93
	v_exp_f32_e32 v94, v94
	v_exp_f32_e32 v95, v95
	s_waitcnt lgkmcnt(8)
	v_mfma_f32_32x32x16_bf16 v[20:35], v[140:143], v[60:63], v[20:35]
	v_exp_f32_e32 v96, v96
	v_exp_f32_e32 v97, v97
	v_exp_f32_e32 v98, v98
	v_exp_f32_e32 v99, v99
	s_waitcnt vmcnt(2) lgkmcnt(0)
	s_barrier
;   #define RESC() do{ if(resc){ asm volatile("s_waitcnt lgkmcnt(0)":::"memory"); \
;       _Pragma("unroll") for(int d_=0;d_<2;++d_) _Pragma("unroll") for(int r=0;r<16;++r)o[d_][r]*=wsf[crow(r,hi)]; } }while(0)
;   #define ROT() do{sl_prev=sl_cur;sl_cur=sl_next;sl_next=(sl_next==(NSLOT-1)*SLOTB)?0:sl_next+SLOTB;}while(0)
;   #define ENDW(tt) do{ if((tt)+3<NT){WAIT_BAR(2);} else if((tt)+2<NT){WAIT_BAR(1);} else {WAIT_BAR(0);} }while(0)
; template<int THRL,bool NOMAX> __device__ __forceinline__ void attn_unit(int b,int h,int qb,int t0,const bf16*Q,const bf16*__restrict__ KV,const bf16*__restrict__ GA,bf16*O,char*shm){
;     ...
;   for(;t+1<NT;t+=2){
;     STEP(pB0,pB1,pA0,pA1,t,(t+3<NT),(t+1<NT),(t+1<NT));       ENDW(t);   RESC(); ROT();
;     STEP(pA0,pA1,pB0,pB1,t+1,(t+4<NT),(t+2<NT),(t+2<NT));     ENDW(t+1); RESC(); ROT();
	ds_read_b64_tr_b16 v[202:203], v2 offset:40960
	ds_read_b64_tr_b16 v[204:205], v2 offset:41472
	v_add_f32_e32 v52, v100, v101
	v_add_f32_e32 v52, v102, v52
	v_add_f32_e32 v52, v103, v52
	v_add_f32_e32 v52, v104, v52
	v_add_f32_e32 v52, v105, v52
	v_cvt_pk_bf16_f32 v160, v100, v101
	v_cvt_pk_bf16_f32 v161, v102, v103
	s_waitcnt lgkmcnt(9)
	v_mfma_f32_32x32x16_bf16 v[116:131], v[64:67], v[152:155], v[36:51]
	ds_read_b64_tr_b16 v[100:101], v2 offset:45056
	ds_read_b64_tr_b16 v[102:103], v2 offset:45568
	v_add_f32_e32 v52, v106, v52
	v_add_f32_e32 v52, v107, v52
	v_add_f32_e32 v52, v108, v52
	v_add_f32_e32 v76, v109, v52
	v_cvt_pk_bf16_f32 v162, v104, v105
	v_cvt_pk_bf16_f32 v163, v106, v107
	s_waitcnt lgkmcnt(10)
	v_mfma_f32_32x32x16_bf16 v[52:67], v[80:83], v[152:155], v[36:51]
	ds_read_b64_tr_b16 v[68:69], v2 offset:41984
	ds_read_b64_tr_b16 v[70:71], v2 offset:42496
	v_add_f32_e32 v76, v110, v76
	v_add_f32_e32 v76, v111, v76
	v_add_f32_e32 v76, v112, v76
	v_add_f32_e32 v80, v113, v76
	v_cvt_pk_bf16_f32 v156, v108, v109
	v_cvt_pk_bf16_f32 v157, v110, v111
	s_waitcnt lgkmcnt(11)
	v_mfma_f32_32x32x16_bf16 v[116:131], v[164:167], v[144:147], v[116:131]
	ds_read_b64_tr_b16 v[76:77], v2 offset:46080
	ds_read_b64_tr_b16 v[78:79], v2 offset:46592
	v_add_f32_e32 v80, v114, v80
	v_add_f32_e32 v80, v115, v80
	v_add_f32_e32 v80, v84, v80
	v_add_f32_e32 v104, v85, v80
	v_cvt_pk_bf16_f32 v158, v112, v113
	v_cvt_pk_bf16_f32 v159, v114, v115
	s_waitcnt lgkmcnt(12)
	v_mfma_f32_32x32x16_bf16 v[52:67], v[168:171], v[144:147], v[52:67]
	ds_read_b64_tr_b16 v[80:81], v2 offset:43008
	ds_read_b64_tr_b16 v[82:83], v2 offset:43520
	v_add_f32_e32 v104, v86, v104
	v_add_f32_e32 v104, v87, v104
	v_add_f32_e32 v104, v88, v104
	v_add_f32_e32 v108, v89, v104
	v_cvt_pk_bf16_f32 v148, v84, v85
	v_cvt_pk_bf16_f32 v149, v86, v87
	s_waitcnt lgkmcnt(13)
	v_mfma_f32_32x32x16_bf16 v[116:131], v[172:175], v[136:139], v[116:131]
	ds_read_b64_tr_b16 v[104:105], v2 offset:47104
	ds_read_b64_tr_b16 v[106:107], v2 offset:47616
	v_add_f32_e32 v84, v90, v108
	v_add_f32_e32 v84, v91, v84
	v_add_f32_e32 v84, v92, v84
	v_add_f32_e32 v84, v93, v84
	v_cvt_pk_bf16_f32 v150, v88, v89
	v_cvt_pk_bf16_f32 v151, v90, v91
	s_waitcnt lgkmcnt(14)
	v_mfma_f32_32x32x16_bf16 v[52:67], v[176:179], v[136:139], v[52:67]
	ds_read_b64_tr_b16 v[88:89], v2 offset:44032
	ds_read_b64_tr_b16 v[90:91], v2 offset:44544
	v_add_f32_e32 v84, v94, v84
	v_add_f32_e32 v84, v95, v84
	v_add_f32_e32 v84, v96, v84
	v_add_f32_e32 v84, v97, v84
	v_cvt_pk_bf16_f32 v140, v92, v93
	v_cvt_pk_bf16_f32 v141, v94, v95
	s_waitcnt lgkmcnt(14)
	v_mfma_f32_32x32x16_bf16 v[116:131], v[198:201], v[132:135], v[116:131]
	ds_read_b64_tr_b16 v[92:93], v2 offset:48128
	ds_read_b64_tr_b16 v[94:95], v2 offset:48640
	v_mfma_f32_32x32x16_bf16 v[52:67], v[72:75], v[132:135], v[52:67]
	v_add_f32_e32 v72, v98, v84
	v_add_f32_e32 v72, v99, v72
	v_add_f32_e32 v72, 0, v72
	v_cvt_pk_bf16_f32 v142, v96, v97
	v_cvt_pk_bf16_f32 v143, v98, v99
	v_readlane_b32 s22, v254, 60
	v_readlane_b32 s23, v254, 61
	s_mov_b32 s23, s17
	v_add_f32_e32 v191, v191, v72
	v_lshl_add_u64 v[72:73], v[182:183], 0, s[22:23]
	s_mov_b32 s14, m0
	s_mov_b32 m0, s9
	s_nop 0
	global_load_lds_dwordx4 v[72:73], off
	s_mov_b32 m0, s14
	s_add_i32 s9, s13, 0x8000
	v_readlane_b32 s14, v254, 62
	v_readlane_b32 s15, v254, 63
	s_mov_b32 s15, s17
	s_mov_b32 s16, s14
	v_lshl_add_u64 v[72:73], v[180:181], 0, s[14:15]
	s_mov_b32 s14, m0
	s_mov_b32 m0, s9
	s_nop 0
	global_load_lds_dwordx4 v[72:73], off
	s_mov_b32 m0, s14
	v_writelane_b32 v254, s16, 62
	s_nop 1
	v_writelane_b32 v254, s17, 63
	s_waitcnt lgkmcnt(14)
	v_mfma_f32_32x32x16_bf16 v[4:19], v[160:163], v[202:205], v[4:19]
	v_exp_f32_e32 v116, v116
	v_exp_f32_e32 v117, v117
	v_exp_f32_e32 v118, v118
	v_exp_f32_e32 v119, v119
	s_waitcnt lgkmcnt(12)
	v_mfma_f32_32x32x16_bf16 v[20:35], v[160:163], v[100:103], v[20:35]
	v_exp_f32_e32 v120, v120
	v_exp_f32_e32 v121, v121
	v_exp_f32_e32 v122, v122
	v_exp_f32_e32 v123, v123
	ds_read_b128 v[72:75], v189 offset:8192
	ds_read_b128 v[96:99], v189 offset:8704
	s_waitcnt lgkmcnt(12)
	v_mfma_f32_32x32x16_bf16 v[4:19], v[156:159], v[68:71], v[4:19]
	v_exp_f32_e32 v124, v124
	v_exp_f32_e32 v125, v125
	v_exp_f32_e32 v126, v126
	v_exp_f32_e32 v127, v127
	ds_read_b128 v[164:167], v189 offset:10240
	ds_read_b128 v[168:171], v189 offset:10752
	s_waitcnt lgkmcnt(12)
	v_mfma_f32_32x32x16_bf16 v[20:35], v[156:159], v[76:79], v[20:35]
	v_exp_f32_e32 v128, v128
	v_exp_f32_e32 v129, v129
	v_exp_f32_e32 v130, v130
	v_exp_f32_e32 v131, v131
	ds_read_b128 v[172:175], v189 offset:12288
	ds_read_b128 v[176:179], v189 offset:12800
	s_waitcnt lgkmcnt(12)
	v_mfma_f32_32x32x16_bf16 v[4:19], v[148:151], v[80:83], v[4:19]
	v_exp_f32_e32 v52, v52
	v_exp_f32_e32 v53, v53
	v_exp_f32_e32 v54, v54
	v_exp_f32_e32 v55, v55
	ds_read_b128 v[198:201], v189 offset:14336
	ds_read_b128 v[84:87], v189 offset:14848
	s_waitcnt lgkmcnt(12)
	v_mfma_f32_32x32x16_bf16 v[20:35], v[148:151], v[104:107], v[20:35]
	v_exp_f32_e32 v56, v56
	v_exp_f32_e32 v57, v57
	v_exp_f32_e32 v58, v58
	v_exp_f32_e32 v59, v59
	s_waitcnt lgkmcnt(10)
	v_mfma_f32_32x32x16_bf16 v[4:19], v[140:143], v[88:91], v[4:19]
	v_exp_f32_e32 v60, v60
	v_exp_f32_e32 v61, v61
	v_exp_f32_e32 v62, v62
	v_exp_f32_e32 v63, v63
	s_waitcnt lgkmcnt(8)
	v_mfma_f32_32x32x16_bf16 v[20:35], v[140:143], v[92:95], v[20:35]
	v_exp_f32_e32 v64, v64
	v_exp_f32_e32 v65, v65
	v_exp_f32_e32 v66, v66
	v_exp_f32_e32 v67, v67
	s_waitcnt vmcnt(2) lgkmcnt(0)
	s_barrier
;   #define RESC() do{ if(resc){ asm volatile("s_waitcnt lgkmcnt(0)":::"memory"); \
;       _Pragma("unroll") for(int d_=0;d_<2;++d_) _Pragma("unroll") for(int r=0;r<16;++r)o[d_][r]*=wsf[crow(r,hi)]; } }while(0)
;   #define ROT() do{sl_prev=sl_cur;sl_cur=sl_next;sl_next=(sl_next==(NSLOT-1)*SLOTB)?0:sl_next+SLOTB;}while(0)
;   #define ENDW(tt) do{ if((tt)+3<NT){WAIT_BAR(2);} else if((tt)+2<NT){WAIT_BAR(1);} else {WAIT_BAR(0);} }while(0)
; template<int THRL,bool NOMAX> __device__ __forceinline__ void attn_unit(int b,int h,int qb,int t0,const bf16*Q,const bf16*__restrict__ KV,const bf16*__restrict__ GA,bf16*O,char*shm){
;     ...
;   for(;t+1<NT;t+=2){
;     STEP(pB0,pB1,pA0,pA1,t,(t+3<NT),(t+1<NT),(t+1<NT));       ENDW(t);   RESC(); ROT();
	ds_read_b64_tr_b16 v[88:89], v2 offset:24576
	ds_read_b64_tr_b16 v[90:91], v2 offset:25088
	v_add_f32_e32 v68, v116, v117
	v_add_f32_e32 v68, v118, v68
	v_add_f32_e32 v68, v119, v68
	v_add_f32_e32 v68, v120, v68
	v_add_f32_e32 v68, v121, v68
	v_cvt_pk_bf16_f32 v160, v116, v117
	v_cvt_pk_bf16_f32 v161, v118, v119
	s_waitcnt lgkmcnt(9)
	v_mfma_f32_32x32x16_bf16 v[100:115], v[72:75], v[152:155], v[36:51]
	ds_read_b64_tr_b16 v[92:93], v2 offset:28672
	ds_read_b64_tr_b16 v[94:95], v2 offset:29184
	v_add_f32_e32 v68, v122, v68
	v_add_f32_e32 v68, v123, v68
	v_add_f32_e32 v68, v124, v68
	v_add_f32_e32 v116, v125, v68
	v_cvt_pk_bf16_f32 v162, v120, v121
	v_cvt_pk_bf16_f32 v163, v122, v123
	s_waitcnt lgkmcnt(10)
	v_mfma_f32_32x32x16_bf16 v[68:83], v[96:99], v[152:155], v[36:51]
	ds_read_b64_tr_b16 v[96:97], v2 offset:25600
	ds_read_b64_tr_b16 v[98:99], v2 offset:26112
	v_add_f32_e32 v116, v126, v116
	v_add_f32_e32 v116, v127, v116
	v_add_f32_e32 v116, v128, v116
	v_add_f32_e32 v120, v129, v116
	v_cvt_pk_bf16_f32 v156, v124, v125
	v_cvt_pk_bf16_f32 v157, v126, v127
	s_waitcnt lgkmcnt(11)
	v_mfma_f32_32x32x16_bf16 v[100:115], v[164:167], v[144:147], v[100:115]
	ds_read_b64_tr_b16 v[116:117], v2 offset:29696
	ds_read_b64_tr_b16 v[118:119], v2 offset:30208
	v_add_f32_e32 v120, v130, v120
	v_add_f32_e32 v120, v131, v120
	v_add_f32_e32 v120, v52, v120
	v_add_f32_e32 v124, v53, v120
	v_cvt_pk_bf16_f32 v158, v128, v129
	v_cvt_pk_bf16_f32 v159, v130, v131
	s_waitcnt lgkmcnt(12)
	v_mfma_f32_32x32x16_bf16 v[68:83], v[168:171], v[144:147], v[68:83]
	ds_read_b64_tr_b16 v[120:121], v2 offset:26624
	ds_read_b64_tr_b16 v[122:123], v2 offset:27136
	v_add_f32_e32 v124, v54, v124
	v_add_f32_e32 v124, v55, v124
	v_add_f32_e32 v124, v56, v124
	v_add_f32_e32 v124, v57, v124
	v_cvt_pk_bf16_f32 v148, v52, v53
	v_cvt_pk_bf16_f32 v149, v54, v55
	s_waitcnt lgkmcnt(13)
	v_mfma_f32_32x32x16_bf16 v[100:115], v[172:175], v[136:139], v[100:115]
	ds_read_b64_tr_b16 v[52:53], v2 offset:30720
	ds_read_b64_tr_b16 v[54:55], v2 offset:31232
	v_add_f32_e32 v124, v58, v124
	v_add_f32_e32 v124, v59, v124
	v_add_f32_e32 v124, v60, v124
	v_add_f32_e32 v124, v61, v124
	v_cvt_pk_bf16_f32 v150, v56, v57
	v_cvt_pk_bf16_f32 v151, v58, v59
	s_waitcnt lgkmcnt(14)
	v_mfma_f32_32x32x16_bf16 v[68:83], v[176:179], v[136:139], v[68:83]
	ds_read_b64_tr_b16 v[56:57], v2 offset:27648
	ds_read_b64_tr_b16 v[58:59], v2 offset:28160
	v_add_f32_e32 v124, v62, v124
	v_add_f32_e32 v124, v63, v124
	v_add_f32_e32 v124, v64, v124
	v_add_f32_e32 v124, v65, v124
	v_cvt_pk_bf16_f32 v140, v60, v61
	v_cvt_pk_bf16_f32 v141, v62, v63
	s_waitcnt lgkmcnt(14)
	v_mfma_f32_32x32x16_bf16 v[100:115], v[198:201], v[132:135], v[100:115]
	ds_read_b64_tr_b16 v[60:61], v2 offset:31744
	ds_read_b64_tr_b16 v[62:63], v2 offset:32256
	v_mfma_f32_32x32x16_bf16 v[68:83], v[84:87], v[132:135], v[68:83]
	v_add_f32_e32 v84, v66, v124
	v_add_f32_e32 v84, v67, v84
	v_add_f32_e32 v84, 0, v84
	v_cvt_pk_bf16_f32 v142, v64, v65
	v_cvt_pk_bf16_f32 v143, v66, v67
	s_mov_b32 s14, s20
	v_lshl_add_u64 v[64:65], v[180:181], 0, s[20:21]
	s_add_i32 s13, s13, 0xa000
	s_mov_b32 s9, m0
	s_mov_b32 m0, s13
	s_nop 0
	global_load_lds_dwordx4 v[64:65], off
	s_mov_b32 m0, s9
	v_writelane_b32 v254, s14, 56
	v_add_f32_e32 v182, v191, v84
	s_nop 0
	v_writelane_b32 v254, s15, 57
	s_waitcnt lgkmcnt(14)
	v_mfma_f32_32x32x16_bf16 v[4:19], v[160:163], v[88:91], v[4:19]
	v_exp_f32_e32 v100, v100
	v_exp_f32_e32 v101, v101
	v_exp_f32_e32 v102, v102
	v_exp_f32_e32 v103, v103
	s_waitcnt lgkmcnt(12)
	v_mfma_f32_32x32x16_bf16 v[20:35], v[160:163], v[92:95], v[20:35]
	v_exp_f32_e32 v104, v104
	v_exp_f32_e32 v105, v105
	v_exp_f32_e32 v106, v106
	v_exp_f32_e32 v107, v107
	ds_read_b128 v[64:67], v189 offset:16384
	ds_read_b128 v[124:127], v189 offset:16896
	s_waitcnt lgkmcnt(12)
	v_mfma_f32_32x32x16_bf16 v[4:19], v[156:159], v[96:99], v[4:19]
	v_exp_f32_e32 v108, v108
	v_exp_f32_e32 v109, v109
	v_exp_f32_e32 v110, v110
	v_exp_f32_e32 v111, v111
	ds_read_b128 v[128:131], v189 offset:18432
	ds_read_b128 v[164:167], v189 offset:18944
	s_waitcnt lgkmcnt(12)
	v_mfma_f32_32x32x16_bf16 v[20:35], v[156:159], v[116:119], v[20:35]
	v_exp_f32_e32 v112, v112
	v_exp_f32_e32 v113, v113
	v_exp_f32_e32 v114, v114
	v_exp_f32_e32 v115, v115
	ds_read_b128 v[168:171], v189 offset:20480
	ds_read_b128 v[172:175], v189 offset:20992
	s_waitcnt lgkmcnt(12)
	v_mfma_f32_32x32x16_bf16 v[4:19], v[148:151], v[120:123], v[4:19]
	v_exp_f32_e32 v68, v68
	v_exp_f32_e32 v69, v69
	v_exp_f32_e32 v70, v70
	v_exp_f32_e32 v71, v71
	ds_read_b128 v[120:123], v189 offset:22528
	ds_read_b128 v[116:119], v189 offset:23040
	s_waitcnt lgkmcnt(12)
	v_mfma_f32_32x32x16_bf16 v[20:35], v[148:151], v[52:55], v[20:35]
	v_exp_f32_e32 v72, v72
	v_exp_f32_e32 v73, v73
	v_exp_f32_e32 v74, v74
	v_exp_f32_e32 v75, v75
	s_waitcnt lgkmcnt(10)
	v_mfma_f32_32x32x16_bf16 v[4:19], v[140:143], v[56:59], v[4:19]
	v_exp_f32_e32 v76, v76
	v_exp_f32_e32 v77, v77
	v_exp_f32_e32 v78, v78
	v_exp_f32_e32 v79, v79
	s_waitcnt lgkmcnt(8)
	v_mfma_f32_32x32x16_bf16 v[20:35], v[140:143], v[60:63], v[20:35]
	v_exp_f32_e32 v80, v80
	v_exp_f32_e32 v81, v81
	v_exp_f32_e32 v82, v82
	v_exp_f32_e32 v83, v83
	s_waitcnt vmcnt(1) lgkmcnt(0)
	s_barrier
;   #define RESC() do{ if(resc){ asm volatile("s_waitcnt lgkmcnt(0)":::"memory"); \
;       _Pragma("unroll") for(int d_=0;d_<2;++d_) _Pragma("unroll") for(int r=0;r<16;++r)o[d_][r]*=wsf[crow(r,hi)]; } }while(0)
;   #define ROT() do{sl_prev=sl_cur;sl_cur=sl_next;sl_next=(sl_next==(NSLOT-1)*SLOTB)?0:sl_next+SLOTB;}while(0)
;   #define ENDW(tt) do{ if((tt)+3<NT){WAIT_BAR(2);} else if((tt)+2<NT){WAIT_BAR(1);} else {WAIT_BAR(0);} }while(0)
; template<int THRL,bool NOMAX> __device__ __forceinline__ void attn_unit(int b,int h,int qb,int t0,const bf16*Q,const bf16*__restrict__ KV,const bf16*__restrict__ GA,bf16*O,char*shm){
;     ...
;   for(;t+1<NT;t+=2){
;     STEP(pB0,pB1,pA0,pA1,t,(t+3<NT),(t+1<NT),(t+1<NT));       ENDW(t);   RESC(); ROT();
;     STEP(pA0,pA1,pB0,pB1,t+1,(t+4<NT),(t+2<NT),(t+2<NT));     ENDW(t+1); RESC(); ROT();
	ds_read_b64_tr_b16 v[176:177], v2 offset:32768
	ds_read_b64_tr_b16 v[178:179], v2 offset:33280
	v_add_f32_e32 v52, v100, v101
	v_add_f32_e32 v52, v102, v52
	v_add_f32_e32 v52, v103, v52
	v_add_f32_e32 v52, v104, v52
	v_add_f32_e32 v52, v105, v52
	v_cvt_pk_bf16_f32 v160, v100, v101
	v_cvt_pk_bf16_f32 v161, v102, v103
	s_waitcnt lgkmcnt(9)
	v_mfma_f32_32x32x16_bf16 v[84:99], v[64:67], v[152:155], v[36:51]
	ds_read_b64_tr_b16 v[100:101], v2 offset:36864
	ds_read_b64_tr_b16 v[102:103], v2 offset:37376
	v_add_f32_e32 v52, v106, v52
	v_add_f32_e32 v52, v107, v52
	v_add_f32_e32 v52, v108, v52
	v_add_f32_e32 v140, v109, v52
	v_cvt_pk_bf16_f32 v162, v104, v105
	v_cvt_pk_bf16_f32 v163, v106, v107
	s_waitcnt lgkmcnt(10)
	v_mfma_f32_32x32x16_bf16 v[52:67], v[124:127], v[152:155], v[36:51]
	ds_read_b64_tr_b16 v[124:125], v2 offset:33792
	ds_read_b64_tr_b16 v[126:127], v2 offset:34304
	v_add_f32_e32 v104, v110, v140
	v_add_f32_e32 v104, v111, v104
	v_add_f32_e32 v104, v112, v104
	v_add_f32_e32 v104, v113, v104
	v_cvt_pk_bf16_f32 v156, v108, v109
	v_cvt_pk_bf16_f32 v157, v110, v111
	s_waitcnt lgkmcnt(11)
	v_mfma_f32_32x32x16_bf16 v[84:99], v[128:131], v[144:147], v[84:99]
	ds_read_b64_tr_b16 v[106:107], v2 offset:37888
	ds_read_b64_tr_b16 v[108:109], v2 offset:38400
	v_add_f32_e32 v104, v114, v104
	v_add_f32_e32 v104, v115, v104
	v_add_f32_e32 v104, v68, v104
	v_add_f32_e32 v104, v69, v104
	v_cvt_pk_bf16_f32 v158, v112, v113
	v_cvt_pk_bf16_f32 v159, v114, v115
	s_waitcnt lgkmcnt(12)
	v_mfma_f32_32x32x16_bf16 v[52:67], v[164:167], v[144:147], v[52:67]
	ds_read_b64_tr_b16 v[110:111], v2 offset:34816
	ds_read_b64_tr_b16 v[112:113], v2 offset:35328
	v_add_f32_e32 v104, v70, v104
	v_add_f32_e32 v104, v71, v104
	v_add_f32_e32 v104, v72, v104
	v_add_f32_e32 v104, v73, v104
	v_cvt_pk_bf16_f32 v148, v68, v69
	v_cvt_pk_bf16_f32 v149, v70, v71
	s_waitcnt lgkmcnt(13)
	v_mfma_f32_32x32x16_bf16 v[84:99], v[168:171], v[136:139], v[84:99]
	ds_read_b64_tr_b16 v[68:69], v2 offset:38912
	ds_read_b64_tr_b16 v[70:71], v2 offset:39424
	v_add_f32_e32 v104, v74, v104
	v_add_f32_e32 v104, v75, v104
	v_add_f32_e32 v104, v76, v104
	v_add_f32_e32 v104, v77, v104
	v_cvt_pk_bf16_f32 v150, v72, v73
	v_cvt_pk_bf16_f32 v151, v74, v75
	s_waitcnt lgkmcnt(14)
	v_mfma_f32_32x32x16_bf16 v[52:67], v[172:175], v[136:139], v[52:67]
	ds_read_b64_tr_b16 v[72:73], v2 offset:35840
	ds_read_b64_tr_b16 v[74:75], v2 offset:36352
	v_add_f32_e32 v104, v78, v104
	v_add_f32_e32 v104, v79, v104
	v_add_f32_e32 v104, v80, v104
	v_add_f32_e32 v104, v81, v104
	v_cvt_pk_bf16_f32 v140, v76, v77
	v_cvt_pk_bf16_f32 v141, v78, v79
	s_waitcnt lgkmcnt(14)
	v_mfma_f32_32x32x16_bf16 v[84:99], v[120:123], v[132:135], v[84:99]
	ds_read_b64_tr_b16 v[76:77], v2 offset:39936
	ds_read_b64_tr_b16 v[78:79], v2 offset:40448
	v_add_f32_e32 v104, v82, v104
	v_add_f32_e32 v104, v83, v104
	v_add_f32_e32 v104, 0, v104
	v_cvt_pk_bf16_f32 v142, v80, v81
	v_cvt_pk_bf16_f32 v143, v82, v83
	v_mfma_f32_32x32x16_bf16 v[52:67], v[116:119], v[132:135], v[52:67]
	s_mov_b32 s14, s22
	v_lshl_add_u64 v[80:81], v[180:181], 0, s[22:23]
	s_mov_b32 s9, m0
	s_mov_b32 m0, s8
	s_nop 0
	global_load_lds_dwordx4 v[80:81], off
	s_mov_b32 m0, s9
	v_writelane_b32 v254, s14, 60
	v_add_f32_e32 v104, v182, v104
	s_nop 0
	v_writelane_b32 v254, s15, 61
	s_waitcnt lgkmcnt(14)
	v_mfma_f32_32x32x16_bf16 v[4:19], v[160:163], v[176:179], v[4:19]
	v_exp_f32_e32 v84, v84
	v_exp_f32_e32 v85, v85
	v_exp_f32_e32 v86, v86
	v_exp_f32_e32 v87, v87
	s_waitcnt lgkmcnt(12)
	v_mfma_f32_32x32x16_bf16 v[20:35], v[160:163], v[100:103], v[20:35]
	v_exp_f32_e32 v88, v88
	v_exp_f32_e32 v89, v89
	v_exp_f32_e32 v90, v90
	v_exp_f32_e32 v91, v91
	ds_read_b128 v[114:117], v189
	ds_read_b128 v[118:121], v189 offset:512
	s_waitcnt lgkmcnt(12)
	v_mfma_f32_32x32x16_bf16 v[4:19], v[156:159], v[124:127], v[4:19]
	v_exp_f32_e32 v92, v92
	v_exp_f32_e32 v93, v93
	v_exp_f32_e32 v94, v94
	v_exp_f32_e32 v95, v95
	ds_read_b128 v[122:125], v189 offset:2048
	ds_read_b128 v[126:129], v189 offset:2560
	s_waitcnt lgkmcnt(12)
	v_mfma_f32_32x32x16_bf16 v[20:35], v[156:159], v[106:109], v[20:35]
	v_exp_f32_e32 v96, v96
	v_exp_f32_e32 v97, v97
	v_exp_f32_e32 v98, v98
	v_exp_f32_e32 v99, v99
	ds_read_b128 v[106:109], v189 offset:4096
	ds_read_b128 v[164:167], v189 offset:4608
	s_waitcnt lgkmcnt(12)
	v_mfma_f32_32x32x16_bf16 v[4:19], v[148:151], v[110:113], v[4:19]
	v_exp_f32_e32 v52, v52
	v_exp_f32_e32 v53, v53
	v_exp_f32_e32 v54, v54
	v_exp_f32_e32 v55, v55
	ds_read_b128 v[110:113], v189 offset:6144
	ds_read_b128 v[100:103], v189 offset:6656
	s_waitcnt lgkmcnt(12)
	v_mfma_f32_32x32x16_bf16 v[20:35], v[148:151], v[68:71], v[20:35]
	v_exp_f32_e32 v56, v56
	v_exp_f32_e32 v57, v57
	v_exp_f32_e32 v58, v58
	v_exp_f32_e32 v59, v59
	s_waitcnt lgkmcnt(10)
	v_mfma_f32_32x32x16_bf16 v[4:19], v[140:143], v[72:75], v[4:19]
	v_exp_f32_e32 v60, v60
	v_exp_f32_e32 v61, v61
	v_exp_f32_e32 v62, v62
	v_exp_f32_e32 v63, v63
	s_waitcnt lgkmcnt(8)
	v_mfma_f32_32x32x16_bf16 v[20:35], v[140:143], v[76:79], v[20:35]
	v_exp_f32_e32 v64, v64
	v_exp_f32_e32 v65, v65
	v_exp_f32_e32 v66, v66
	v_exp_f32_e32 v67, v67
	s_waitcnt vmcnt(0) lgkmcnt(0)
	s_barrier
;   #define RESC() do{ if(resc){ asm volatile("s_waitcnt lgkmcnt(0)":::"memory"); \
;       _Pragma("unroll") for(int d_=0;d_<2;++d_) _Pragma("unroll") for(int r=0;r<16;++r)o[d_][r]*=wsf[crow(r,hi)]; } }while(0)
; template<int THRL,bool NOMAX> __device__ __forceinline__ void attn_unit(int b,int h,int qb,int t0,const bf16*Q,const bf16*__restrict__ KV,const bf16*__restrict__ GA,bf16*O,char*shm){
;     ...
;   STEP(pB0,pB1,pA0,pA1,NT-1,false,false,false); RESC();
	ds_read_b64_tr_b16 v[168:169], v2 offset:40960
	ds_read_b64_tr_b16 v[170:171], v2 offset:41472
	v_add_f32_e32 v68, v84, v85
	v_add_f32_e32 v68, v86, v68
	v_add_f32_e32 v68, v87, v68
	v_add_f32_e32 v68, v88, v68
	v_add_f32_e32 v105, v89, v68
	v_cvt_pk_bf16_f32 v160, v84, v85
	v_cvt_pk_bf16_f32 v161, v86, v87
	s_waitcnt lgkmcnt(9)
	v_mfma_f32_32x32x16_bf16 v[68:83], v[114:117], v[152:155], v[36:51]
	ds_read_b64_tr_b16 v[84:85], v2 offset:45056
	ds_read_b64_tr_b16 v[86:87], v2 offset:45568
	s_waitcnt lgkmcnt(10)
	v_mfma_f32_32x32x16_bf16 v[36:51], v[118:121], v[152:155], v[36:51]
	v_add_f32_e32 v105, v90, v105
	v_add_f32_e32 v105, v91, v105
	v_add_f32_e32 v105, v92, v105
	v_add_f32_e32 v105, v93, v105
	v_cvt_pk_bf16_f32 v162, v88, v89
	v_cvt_pk_bf16_f32 v163, v90, v91
	ds_read_b64_tr_b16 v[88:89], v2 offset:41984
	ds_read_b64_tr_b16 v[90:91], v2 offset:42496
	v_add_f32_e32 v105, v94, v105
	v_add_f32_e32 v105, v95, v105
	v_add_f32_e32 v105, v96, v105
	v_add_f32_e32 v105, v97, v105
	v_cvt_pk_bf16_f32 v156, v92, v93
	v_cvt_pk_bf16_f32 v157, v94, v95
	s_waitcnt lgkmcnt(11)
	v_mfma_f32_32x32x16_bf16 v[68:83], v[122:125], v[144:147], v[68:83]
	ds_read_b64_tr_b16 v[92:93], v2 offset:46080
	ds_read_b64_tr_b16 v[94:95], v2 offset:46592
	s_waitcnt lgkmcnt(12)
	v_mfma_f32_32x32x16_bf16 v[36:51], v[126:129], v[144:147], v[36:51]
	v_add_f32_e32 v105, v98, v105
	v_add_f32_e32 v105, v99, v105
	v_add_f32_e32 v105, v52, v105
	v_add_f32_e32 v105, v53, v105
	v_cvt_pk_bf16_f32 v158, v96, v97
	v_cvt_pk_bf16_f32 v159, v98, v99
	ds_read_b64_tr_b16 v[96:97], v2 offset:43008
	ds_read_b64_tr_b16 v[98:99], v2 offset:43520
	v_add_f32_e32 v105, v54, v105
	v_add_f32_e32 v105, v55, v105
	v_add_f32_e32 v105, v56, v105
	v_add_f32_e32 v105, v57, v105
	v_cvt_pk_bf16_f32 v148, v52, v53
	v_cvt_pk_bf16_f32 v149, v54, v55
	s_waitcnt lgkmcnt(13)
	v_mfma_f32_32x32x16_bf16 v[68:83], v[106:109], v[136:139], v[68:83]
	ds_read_b64_tr_b16 v[52:53], v2 offset:47104
	ds_read_b64_tr_b16 v[54:55], v2 offset:47616
	s_waitcnt lgkmcnt(14)
	v_mfma_f32_32x32x16_bf16 v[36:51], v[164:167], v[136:139], v[36:51]
	v_add_f32_e32 v105, v58, v105
	v_add_f32_e32 v105, v59, v105
	v_add_f32_e32 v105, v60, v105
	v_add_f32_e32 v105, v61, v105
	v_cvt_pk_bf16_f32 v150, v56, v57
	v_cvt_pk_bf16_f32 v151, v58, v59
	ds_read_b64_tr_b16 v[56:57], v2 offset:44032
	ds_read_b64_tr_b16 v[58:59], v2 offset:44544
	v_add_f32_e32 v105, v62, v105
	v_add_f32_e32 v105, v63, v105
	v_add_f32_e32 v105, v64, v105
	v_add_f32_e32 v105, v65, v105
	v_cvt_pk_bf16_f32 v140, v60, v61
	v_cvt_pk_bf16_f32 v141, v62, v63
	s_waitcnt lgkmcnt(14)
	v_mfma_f32_32x32x16_bf16 v[68:83], v[110:113], v[132:135], v[68:83]
	ds_read_b64_tr_b16 v[60:61], v2 offset:48128
	ds_read_b64_tr_b16 v[62:63], v2 offset:48640
	v_mfma_f32_32x32x16_bf16 v[36:51], v[100:103], v[132:135], v[36:51]
	v_add_f32_e32 v2, v66, v105
	v_add_f32_e32 v2, v67, v2
	v_add_f32_e32 v2, 0, v2
	v_cvt_pk_bf16_f32 v142, v64, v65
	v_cvt_pk_bf16_f32 v143, v66, v67
	s_waitcnt lgkmcnt(14)
	v_mfma_f32_32x32x16_bf16 v[4:19], v[160:163], v[168:171], v[4:19]
	s_nop 1
	v_exp_f32_e32 v68, v68
	v_exp_f32_e32 v69, v69
	v_exp_f32_e32 v70, v70
	v_exp_f32_e32 v71, v71
	s_waitcnt lgkmcnt(12)
	v_mfma_f32_32x32x16_bf16 v[20:35], v[160:163], v[84:87], v[20:35]
	v_exp_f32_e32 v72, v72
	v_exp_f32_e32 v73, v73
	v_exp_f32_e32 v74, v74
	v_exp_f32_e32 v75, v75
	s_waitcnt lgkmcnt(10)
	v_mfma_f32_32x32x16_bf16 v[4:19], v[156:159], v[88:91], v[4:19]
	v_exp_f32_e32 v76, v76
	v_exp_f32_e32 v77, v77
	v_exp_f32_e32 v78, v78
	v_exp_f32_e32 v79, v79
	s_waitcnt lgkmcnt(8)
	v_mfma_f32_32x32x16_bf16 v[20:35], v[156:159], v[92:95], v[20:35]
	v_exp_f32_e32 v80, v80
	v_exp_f32_e32 v81, v81
	v_exp_f32_e32 v82, v82
	v_exp_f32_e32 v83, v83
	s_waitcnt lgkmcnt(6)
; #define SBAR() __builtin_amdgcn_sched_barrier(0)
;   #define RESC() do{ if(resc){ asm volatile("s_waitcnt lgkmcnt(0)":::"memory"); \
;       _Pragma("unroll") for(int d_=0;d_<2;++d_) _Pragma("unroll") for(int r=0;r<16;++r)o[d_][r]*=wsf[crow(r,hi)]; } }while(0)
;   #define PKW(P,B) cvtpk_s(P[B],P[B+1])
; __device__ __forceinline__ void pv(f32x16*o,int vb,bf16x8 pa0,bf16x8 pa1,bf16x8 pa2,bf16x8 pa3){
;   #pragma unroll
;   for(int d0=0;d0<2;++d0){s16x4 lo[4],hi[4];
;     #pragma unroll
;     for(int ks=0;ks<4;++ks){
;       asm volatile("ds_read_b64_tr_b16 %0,%1 offset:%c2":"=&v"(lo[ks]):"v"(vb),"i"(d0*4096+ks*1024):"memory");
;       asm volatile("ds_read_b64_tr_b16 %0,%1 offset:%c2":"=&v"(hi[ks]):"v"(vb),"i"(d0*4096+ks*1024+512):"memory");}
;     asm volatile("s_waitcnt lgkmcnt(0)":::"memory");SBAR();
;     ...
;     o[d0]=__builtin_amdgcn_mfma_f32_32x32x16_bf16(pa0,PK(0),o[d0],0,0,0);
;     o[d0]=__builtin_amdgcn_mfma_f32_32x32x16_bf16(pa1,PK(1),o[d0],0,0,0);
;     o[d0]=__builtin_amdgcn_mfma_f32_32x32x16_bf16(pa2,PK(2),o[d0],0,0,0);
;     o[d0]=__builtin_amdgcn_mfma_f32_32x32x16_bf16(pa3,PK(3),o[d0],0,0,0);
;     ...
;   }
; }
; template<int THRL,bool NOMAX> __device__ __forceinline__ void attn_unit(int b,int h,int qb,int t0,const bf16*Q,const bf16*__restrict__ KV,const bf16*__restrict__ GA,bf16*O,char*shm){
;     ...
;   STEP(pB0,pB1,pA0,pA1,NT-1,false,false,false); RESC();
;   { float sacc=pB0[0]+pB0[1]; _Pragma("unroll") for(int r=2;r<16;++r)sacc+=pB0[r]; _Pragma("unroll") for(int r=0;r<16;++r)sacc+=pB1[r]; l_reg+=sacc;
;     pw0=(u32x4){PKW(pB0,0),PKW(pB0,2),PKW(pB0,4),PKW(pB0,6)};pw1=(u32x4){PKW(pB0,8),PKW(pB0,10),PKW(pB0,12),PKW(pB0,14)};pw2=(u32x4){PKW(pB1,0),PKW(pB1,2),PKW(pB1,4),PKW(pB1,6)};pw3=(u32x4){PKW(pB1,8),PKW(pB1,10),PKW(pB1,12),PKW(pB1,14)};
;     SBAR(); pv(o,vb0+sl_cur,PAF(0),PAF(1),PAF(2),PAF(3)); }
;     ...
;   {auto rr=__builtin_amdgcn_permlane32_swap(__float_as_uint(l_reg),__float_as_uint(l_reg),false,false);l_reg=__uint_as_float(rr[0])+__uint_as_float(rr[1]);}
;   if(hi==0)wsf[32+r32]=l_reg;asm volatile("s_waitcnt lgkmcnt(0)":::"memory");
	v_mfma_f32_32x32x16_bf16 v[4:19], v[148:151], v[96:99], v[4:19]
	v_exp_f32_e32 v36, v36
	v_exp_f32_e32 v37, v37
	v_exp_f32_e32 v38, v38
	v_exp_f32_e32 v39, v39
	s_waitcnt lgkmcnt(4)
	v_mfma_f32_32x32x16_bf16 v[20:35], v[148:151], v[52:55], v[20:35]
	v_exp_f32_e32 v40, v40
	v_exp_f32_e32 v41, v41
	v_exp_f32_e32 v42, v42
	v_exp_f32_e32 v43, v43
	s_waitcnt lgkmcnt(2)
	v_mfma_f32_32x32x16_bf16 v[4:19], v[140:143], v[56:59], v[4:19]
	v_exp_f32_e32 v44, v44
	v_exp_f32_e32 v45, v45
	v_exp_f32_e32 v46, v46
	v_exp_f32_e32 v47, v47
	s_waitcnt lgkmcnt(0)
	v_mfma_f32_32x32x16_bf16 v[20:35], v[140:143], v[60:63], v[20:35]
	v_exp_f32_e32 v48, v48
	v_exp_f32_e32 v49, v49
	v_exp_f32_e32 v50, v50
	v_exp_f32_e32 v51, v51
	v_add_f32_e32 v52, v68, v69
	v_add_f32_e32 v52, v70, v52
	v_add_f32_e32 v52, v71, v52
	v_add_f32_e32 v52, v72, v52
	v_add_f32_e32 v52, v73, v52
	v_add_f32_e32 v52, v74, v52
	v_add_f32_e32 v52, v75, v52
	v_add_f32_e32 v52, v76, v52
	v_add_f32_e32 v52, v77, v52
	v_add_f32_e32 v52, v78, v52
	v_add_f32_e32 v52, v79, v52
	v_add_f32_e32 v52, v80, v52
	v_add_f32_e32 v52, v81, v52
	v_add_f32_e32 v52, v82, v52
	v_add_f32_e32 v52, v83, v52
	v_add_f32_e32 v52, v36, v52
	v_add_f32_e32 v52, v37, v52
	v_add_f32_e32 v52, v38, v52
	v_add_f32_e32 v52, v39, v52
	v_add_f32_e32 v52, v40, v52
	v_add_f32_e32 v52, v41, v52
	v_add_f32_e32 v52, v42, v52
	v_add_f32_e32 v52, v43, v52
	v_add_f32_e32 v52, v44, v52
	v_add_f32_e32 v52, v45, v52
	v_add_f32_e32 v52, v46, v52
	v_add_f32_e32 v52, v47, v52
	v_add_f32_e32 v52, v48, v52
	v_add_f32_e32 v52, v49, v52
	v_add_f32_e32 v52, v50, v52
	v_add_f32_e32 v52, v51, v52
	v_add_f32_e32 v2, v104, v2
	v_add_f32_e32 v2, v2, v52
	v_cvt_pk_bf16_f32 v36, v36, v37
	v_cvt_pk_bf16_f32 v52, v68, v69
	v_cvt_pk_bf16_f32 v53, v70, v71
	v_cvt_pk_bf16_f32 v54, v72, v73
	v_cvt_pk_bf16_f32 v55, v74, v75
	v_cvt_pk_bf16_f32 v56, v76, v77
	v_cvt_pk_bf16_f32 v57, v78, v79
	v_cvt_pk_bf16_f32 v58, v80, v81
	v_cvt_pk_bf16_f32 v59, v82, v83
	v_cvt_pk_bf16_f32 v37, v38, v39
	v_cvt_pk_bf16_f32 v38, v40, v41
	v_cvt_pk_bf16_f32 v39, v42, v43
	v_cvt_pk_bf16_f32 v40, v44, v45
	v_cvt_pk_bf16_f32 v41, v46, v47
	v_cvt_pk_bf16_f32 v42, v48, v49
	v_cvt_pk_bf16_f32 v43, v50, v51
	ds_read_b64_tr_b16 v[44:45],v190 offset:0
	ds_read_b64_tr_b16 v[46:47],v190 offset:512
	ds_read_b64_tr_b16 v[48:49],v190 offset:1024
	ds_read_b64_tr_b16 v[50:51],v190 offset:1536
	ds_read_b64_tr_b16 v[60:61],v190 offset:2048
	ds_read_b64_tr_b16 v[62:63],v190 offset:2560
	ds_read_b64_tr_b16 v[64:65],v190 offset:3072
	ds_read_b64_tr_b16 v[66:67],v190 offset:3584
	s_waitcnt lgkmcnt(0)
	s_nop 0
	v_mfma_f32_32x32x16_bf16 v[4:19], v[52:55], v[44:47], v[4:19]
	ds_read_b64_tr_b16 v[44:45],v190 offset:4096
	ds_read_b64_tr_b16 v[46:47],v190 offset:4608
	v_mfma_f32_32x32x16_bf16 v[4:19], v[56:59], v[48:51], v[4:19]
	ds_read_b64_tr_b16 v[48:49],v190 offset:5120
	ds_read_b64_tr_b16 v[50:51],v190 offset:5632
	v_mfma_f32_32x32x16_bf16 v[4:19], v[36:39], v[60:63], v[4:19]
	ds_read_b64_tr_b16 v[60:61],v190 offset:6144
	ds_read_b64_tr_b16 v[62:63],v190 offset:6656
	v_mfma_f32_32x32x16_bf16 v[4:19], v[40:43], v[64:67], v[4:19]
	ds_read_b64_tr_b16 v[64:65],v190 offset:7168
	ds_read_b64_tr_b16 v[66:67],v190 offset:7680
	s_waitcnt lgkmcnt(0)
	v_mfma_f32_32x32x16_bf16 v[20:35], v[52:55], v[44:47], v[20:35]
	v_cmp_gt_u32_e32 vcc, 32, v184
	v_mfma_f32_32x32x16_bf16 v[20:35], v[56:59], v[48:51], v[20:35]
	v_mfma_f32_32x32x16_bf16 v[20:35], v[36:39], v[60:63], v[20:35]
	v_mov_b32_e32 v36, v2
	s_nop 1
	v_permlane32_swap_b32_e32 v2, v36
	v_mfma_f32_32x32x16_bf16 v[20:35], v[40:43], v[64:67], v[20:35]
	s_and_saveexec_b64 s[8:9], vcc
	s_cbranch_execz .LBB0_470
	v_lshl_add_u32 v37, v185, 2, s12
	v_add_f32_e32 v2, v2, v36
	ds_write_b32 v37, v2 offset:49280
	s_branch .LBB0_470
